# speedup vs baseline: 1.0059x; 1.0059x over previous
; __device__ __forceinline__ int v_st(int k, int c) { const int kk = (k & ~0xC) | ((k & 4) << 1) | ((k & 8) >> 1); return ((kk >> 3) * 2 + (c >> 5)) * 512 + ((kk & 7) * 32 + (c & 31)) * 2; }
; __device__ __forceinline__ int v_rd_base(int lane) { return ((lane & 3) << 3) | (((lane >> 2) & 3) << 6) | (((lane >> 4) & 1) << 5) | (((lane >> 5) & 1) << 8); }
; #define SLOADP(i, Kp, Vp, t) do { const char* kp = (const char*)(Kp) + (long)(t) * (64 * 192); const char* vp = (const char*)(Vp) + (long)(t) * (64 * 128); \
;     sr_[i].k0 = *reinterpret_cast<const bf16x8*>(kp + kc0 * 16); sr_[i].k1 = *reinterpret_cast<const bf16x8*>(kp + kc1 * 16); \
;     sr_[i].v0 = *reinterpret_cast<const bf16x8*>(vp + tid * 16); } while (0)
; __device__ __forceinline__ void attn_phase(const bf16* __restrict__ qbase, const bf16* __restrict__ Kbase, const bf16* __restrict__ Vbase, bf16* __restrict__ mixbase) {
;     ...
;   int it = vtile(0); if (it >= nend) return;
;   char* lds = shm_raw;
;   const int tid = threadIdx.x, wid = tid >> 6, lane = tid & 63, r32 = lane & 31, hi = lane >> 5;
;   char* V_lds = lds + ATT_V0; char* K_lds = lds + ATT_K0;
;   float* wsf = (float*)(lds + ATT_WS) + wid * 64; float* al_l = wsf + 32;
;   const int kc0 = tid, kc1 = 512 + (tid & 255);
;   const int kst0 = (kc0 / 12) * KPITCH + (kc0 % 12) * 16, kst1 = (kc1 / 12) * KPITCH + (kc1 % 12) * 16;
;   const int vst = v_st(tid >> 3, (tid & 7) * 8);
;   const int vb0 = (int)(uintptr_t)V_lds + v_rd_base(lane);
;   const short one_ = (r32 == 0) ? (short)0x3F80 : (short)0; const bf16x8 ones = {one_, one_, one_, one_, one_, one_, one_, one_};
;   struct { bf16x8 k0, k1, v0; } sr_[2];
;   bf16x8 qr[6];
;   constexpr int SE = 0, SO = 1;
;     ...
;   const bf16 *Qw, *Kh, *Vh; bf16* Ob;
;   ITEM_PTRS(it, Qw, Kh, Vh, Ob);
;   #pragma unroll
;   for (int d0 = 0; d0 < 6; ++d0) qr[d0] = *reinterpret_cast<const bf16x8*>(Qw + d0 * 16);
;   SLOADP(SO, Kh, Vh, 0); SLOADP(SE, Kh, Vh, 1);
;   if (wid >= 4) __builtin_amdgcn_s_setprio(1);
.LBB0_505:
	s_or_b64 exec, exec, s[0:1]
	v_readlane_b32 s82, v254, 36
	v_readlane_b32 s84, v254, 39
	s_cmpk_lt_i32 s95, 0xc00
	v_readlane_b32 s83, v254, 37
	v_readlane_b32 s77, v254, 38
	v_readlane_b32 s85, v254, 40
	s_barrier
	s_cbranch_scc0 .LBB0_542
	s_movk_i32 s0, 0x200
	v_or_b32_sdwa v3, v252, s0 dst_sel:DWORD dst_unused:UNUSED_PAD src0_sel:BYTE_0 src1_sel:DWORD
	s_ashr_i32 s6, s95, 3
	s_ashr_i32 s0, s95, 6
	s_lshl_b32 s5, s95, 8
	v_and_b32_e32 v0, 31, v252
	v_lshrrev_b32_e32 v2, 1, v252
	s_and_b32 s4, s6, 7
	s_ashr_i32 s1, s0, 31
	s_mul_i32 s2, s0, 0x810
	s_and_b32 s5, s5, 0x700
	v_add_u32_e32 v4, 16, v0
	v_and_b32_e32 v2, 0x1e0, v2
	v_mov_b32_e32 v165, 0
	s_mul_hi_i32 s3, s0, 0x810
	s_add_u32 s2, s5, s2
	v_add_u32_e32 v162, v4, v2
	v_mov_b32_e32 v163, v165
	s_addc_u32 s3, 0, s3
	v_lshl_add_u64 v[4:5], s[2:3], 0, v[162:163]
	s_movk_i32 s8, 0x600
	v_mov_b64_e32 v[6:7], s[34:35]
	s_mov_b32 s40, 0
	v_mad_u64_u32 v[6:7], s[2:3], v4, s8, v[6:7]
	v_mad_i32_i24 v7, v5, s8, v7
	s_mul_i32 s2, s4, 0xc0
	s_mov_b32 s3, s40
	v_lshrrev_b32_e32 v1, 5, v193
	v_lshl_add_u64 v[168:169], v[6:7], 0, s[2:3]
	s_mul_hi_i32 s2, s6, 0x63000
	s_mul_i32 s3, s6, 0x63000
	s_mul_hi_i32 s9, s6, 0x42000
	s_mul_i32 s10, s6, 0x42000
	v_readlane_b32 s6, v254, 23
	v_lshlrev_b32_e32 v170, 4, v1
	v_mov_b32_e32 v171, v165
	v_readlane_b32 s7, v254, 24
	s_add_u32 s6, s6, s3
	v_lshl_add_u64 v[4:5], v[168:169], 0, v[170:171]
	s_addc_u32 s7, s7, s2
	global_load_dwordx4 v[80:83], v[4:5], off
	global_load_dwordx4 v[84:87], v[4:5], off offset:32
	global_load_dwordx4 v[88:91], v[4:5], off offset:64
	global_load_dwordx4 v[92:95], v[4:5], off offset:96
	global_load_dwordx4 v[96:99], v[4:5], off offset:128
	global_load_dwordx4 v[100:103], v[4:5], off offset:160
	s_add_u32 s60, s64, s10
	v_lshlrev_b32_e32 v160, 4, v252
	v_mov_b32_e32 v161, v165
	s_addc_u32 s61, s65, s9
	v_lshl_add_u64 v[4:5], s[60:61], 0, v[160:161]
	s_add_u32 s2, s6, 0x3000
	v_lshlrev_b32_e32 v166, 4, v3
	s_addc_u32 s3, s7, 0
	v_add_co_u32_e32 v4, vcc, 0x2000, v4
	global_load_dwordx4 v[132:135], v160, s[6:7]
	global_load_dwordx4 v[136:139], v160, s[60:61]
	global_load_dwordx4 v[140:143], v166, s[6:7]
	global_load_dwordx4 v[104:107], v160, s[2:3]
	v_addc_co_u32_e32 v5, vcc, 0, v5, vcc
	global_load_dwordx4 v[108:111], v166, s[2:3]
	global_load_dwordx4 v[112:115], v[4:5], off
	s_movk_i32 s2, 0xff
	v_lshlrev_b32_e32 v4, 3, v1
	v_cmp_ge_u32_e32 vcc, s2, v252
	s_and_saveexec_b64 s[2:3], vcc
	s_cbranch_execz .Latt_prio_done
	s_setprio 1
